# P1 GEMM: peeled first K iteration with C=0, no accumulator zeroing
# speedup vs baseline: 1.0262x; 1.0037x over previous
.LBB0_130:
	s_ashr_i32 s13, s12, 31
	s_lshl_b64 s[14:15], s[12:13], 19
	v_readlane_b32 s16, v254, 39
	v_readlane_b32 s17, v254, 40
	s_add_u32 s14, s16, s14
	s_addc_u32 s15, s17, s15
	s_and_b64 s[16:17], s[0:1], exec
	s_cselect_b32 s13, s15, s19
	s_cselect_b32 s42, s14, s18
	s_ashr_i32 s11, s10, 31
	s_lshl_b64 s[16:17], s[10:11], 19
	s_add_u32 s16, s24, s16
	s_addc_u32 s17, s25, s17
	s_and_b64 s[22:23], s[0:1], exec
	s_cselect_b32 s11, s17, s21
	s_cselect_b32 s43, s16, s20
	s_add_u32 s18, s18, 0x40080
	s_addc_u32 s19, s19, 0
	s_add_u32 s44, s20, 0x100
	s_addc_u32 s45, s21, 0
	s_mov_b32 s46, -2
	ds_read_b128 v[152:155], v148
	ds_read_b128 v[156:159], v148 offset:1024
	ds_read_b128 v[160:163], v148 offset:2048
	ds_read_b128 v[164:167], v148 offset:3072
	ds_read_b128 v[168:171], v149
	ds_read_b128 v[172:175], v149 offset:1024
	ds_read_b128 v[176:179], v149 offset:2048
	ds_read_b128 v[180:183], v149 offset:3072
	s_add_u32 s20, s18, 0xfffc0080
	s_addc_u32 s21, s19, -1
	s_cmp_eq_u32 s46, 12
	s_cselect_b32 s23, s13, s21
	s_cselect_b32 s22, s42, s20
	s_cselect_b32 s21, s11, s45
	s_cselect_b32 s20, s43, s44
	v_lshl_add_u64 v[216:217], s[18:19], 0, v[136:137]
	s_add_i32 m0, s9, 0xc000
	ds_read_b128 v[184:187], v150
	ds_read_b128 v[188:191], v150 offset:1024
	ds_read_b128 v[192:195], v150 offset:2048
	ds_read_b128 v[196:199], v150 offset:3072
	ds_read_b128 v[200:203], v150 offset:4096
	ds_read_b128 v[204:207], v150 offset:5120
	ds_read_b128 v[208:211], v150 offset:6144
	ds_read_b128 v[212:215], v150 offset:7168
	global_load_lds_dwordx4 v[216:217], off
	v_lshl_add_u64 v[216:217], s[18:19], 0, v[138:139]
	s_add_i32 m0, s9, 0xe000
	s_nop 0
	global_load_lds_dwordx4 v[216:217], off
	s_waitcnt vmcnt(8)
	s_waitcnt lgkmcnt(0)
	s_barrier
	s_setprio 1
	s_waitcnt lgkmcnt(0)
	v_mfma_f32_16x16x32_bf16 v[124:127], v[152:155], v[184:187], 0
	v_mfma_f32_16x16x32_bf16 v[120:123], v[160:163], v[184:187], 0
	v_mfma_f32_16x16x32_bf16 v[116:119], v[152:155], v[192:195], 0
	v_mfma_f32_16x16x32_bf16 v[112:115], v[160:163], v[192:195], 0
	v_mfma_f32_16x16x32_bf16 v[100:103], v[152:155], v[200:203], 0
	v_mfma_f32_16x16x32_bf16 v[96:99], v[160:163], v[200:203], 0
	v_mfma_f32_16x16x32_bf16 v[84:87], v[152:155], v[208:211], 0
	v_mfma_f32_16x16x32_bf16 v[80:83], v[160:163], v[208:211], 0
	v_mfma_f32_16x16x32_bf16 v[124:127], v[156:159], v[188:191], v[124:127]
	v_mfma_f32_16x16x32_bf16 v[120:123], v[164:167], v[188:191], v[120:123]
	v_mfma_f32_16x16x32_bf16 v[116:119], v[156:159], v[196:199], v[116:119]
	v_mfma_f32_16x16x32_bf16 v[112:115], v[164:167], v[196:199], v[112:115]
	v_mfma_f32_16x16x32_bf16 v[100:103], v[156:159], v[204:207], v[100:103]
	v_mfma_f32_16x16x32_bf16 v[96:99], v[164:167], v[204:207], v[96:99]
	v_mfma_f32_16x16x32_bf16 v[84:87], v[156:159], v[212:215], v[84:87]
	v_mfma_f32_16x16x32_bf16 v[80:83], v[164:167], v[212:215], v[80:83]
	s_setprio 0
	s_setprio 1
	v_mfma_f32_16x16x32_bf16 v[108:111], v[168:171], v[184:187], 0
	v_mfma_f32_16x16x32_bf16 v[104:107], v[176:179], v[184:187], 0
	v_mfma_f32_16x16x32_bf16 v[92:95], v[168:171], v[192:195], 0
	v_mfma_f32_16x16x32_bf16 v[88:91], v[176:179], v[192:195], 0
	v_mfma_f32_16x16x32_bf16 v[76:79], v[168:171], v[200:203], 0
	v_mfma_f32_16x16x32_bf16 v[72:75], v[176:179], v[200:203], 0
	v_mfma_f32_16x16x32_bf16 v[68:71], v[168:171], v[208:211], 0
	v_mfma_f32_16x16x32_bf16 v[64:67], v[176:179], v[208:211], 0
	v_mfma_f32_16x16x32_bf16 v[108:111], v[172:175], v[188:191], v[108:111]
	v_mfma_f32_16x16x32_bf16 v[104:107], v[180:183], v[188:191], v[104:107]
	v_mfma_f32_16x16x32_bf16 v[92:95], v[172:175], v[196:199], v[92:95]
	v_mfma_f32_16x16x32_bf16 v[88:91], v[180:183], v[196:199], v[88:91]
	v_mfma_f32_16x16x32_bf16 v[76:79], v[172:175], v[204:207], v[76:79]
	v_mfma_f32_16x16x32_bf16 v[72:75], v[180:183], v[204:207], v[72:75]
	v_mfma_f32_16x16x32_bf16 v[68:71], v[172:175], v[212:215], v[68:71]
	v_mfma_f32_16x16x32_bf16 v[64:67], v[180:183], v[212:215], v[64:67]
	s_setprio 0
	s_barrier
	s_add_i32 s47, s38, s26
	v_lshl_add_u64 v[216:217], s[20:21], 0, v[132:133]
	s_mov_b32 m0, s47
	ds_read_b128 v[184:187], v150 offset:16384
	ds_read_b128 v[188:191], v150 offset:17408
	ds_read_b128 v[192:195], v150 offset:18432
	ds_read_b128 v[196:199], v150 offset:19456
	ds_read_b128 v[200:203], v150 offset:20480
	ds_read_b128 v[204:207], v150 offset:21504
	ds_read_b128 v[208:211], v150 offset:22528
	ds_read_b128 v[212:215], v150 offset:23552
	global_load_lds_dwordx4 v[216:217], off
	s_add_i32 m0, s47, 0x2000
	s_add_u32 s48, s20, 0x40000
	v_lshl_add_u64 v[218:219], s[20:21], 0, v[128:129]
	s_addc_u32 s49, s21, 0
	s_add_i32 s47, s39, s26
	global_load_lds_dwordx4 v[218:219], off
	v_lshl_add_u64 v[220:221], s[48:49], 0, v[132:133]
	s_mov_b32 m0, s47
	v_lshl_add_u64 v[222:223], s[22:23], 0, v[130:131]
	global_load_lds_dwordx4 v[220:221], off
	v_lshl_add_u64 v[220:221], s[48:49], 0, v[128:129]
	s_add_i32 m0, s47, 0x2000
	s_nop 0
	global_load_lds_dwordx4 v[220:221], off
	v_lshl_add_u64 v[220:221], s[22:23], 0, v[134:135]
	s_mov_b32 m0, s9
	s_nop 0
	global_load_lds_dwordx4 v[220:221], off
	s_mov_b32 m0, s29
	s_nop 0
	global_load_lds_dwordx4 v[222:223], off
	s_waitcnt vmcnt(8)
	s_waitcnt lgkmcnt(0)
	s_barrier
	s_setprio 1
	s_waitcnt lgkmcnt(0)
	v_mfma_f32_16x16x32_bf16 v[60:63], v[152:155], v[184:187], 0
	v_mfma_f32_16x16x32_bf16 v[56:59], v[160:163], v[184:187], 0
	v_mfma_f32_16x16x32_bf16 v[52:55], v[152:155], v[192:195], 0
	v_mfma_f32_16x16x32_bf16 v[48:51], v[160:163], v[192:195], 0
	v_mfma_f32_16x16x32_bf16 v[36:39], v[152:155], v[200:203], 0
	v_mfma_f32_16x16x32_bf16 v[32:35], v[160:163], v[200:203], 0
	v_mfma_f32_16x16x32_bf16 v[20:23], v[152:155], v[208:211], 0
	v_mfma_f32_16x16x32_bf16 v[16:19], v[160:163], v[208:211], 0
	v_mfma_f32_16x16x32_bf16 v[60:63], v[156:159], v[188:191], v[60:63]
	v_mfma_f32_16x16x32_bf16 v[56:59], v[164:167], v[188:191], v[56:59]
	v_mfma_f32_16x16x32_bf16 v[52:55], v[156:159], v[196:199], v[52:55]
	v_mfma_f32_16x16x32_bf16 v[48:51], v[164:167], v[196:199], v[48:51]
	v_mfma_f32_16x16x32_bf16 v[36:39], v[156:159], v[204:207], v[36:39]
	v_mfma_f32_16x16x32_bf16 v[32:35], v[164:167], v[204:207], v[32:35]
	v_mfma_f32_16x16x32_bf16 v[20:23], v[156:159], v[212:215], v[20:23]
	v_mfma_f32_16x16x32_bf16 v[16:19], v[164:167], v[212:215], v[16:19]
	s_setprio 0
	s_setprio 1
	v_mfma_f32_16x16x32_bf16 v[44:47], v[168:171], v[184:187], 0
	v_mfma_f32_16x16x32_bf16 v[40:43], v[176:179], v[184:187], 0
	v_mfma_f32_16x16x32_bf16 v[28:31], v[168:171], v[192:195], 0
	v_mfma_f32_16x16x32_bf16 v[24:27], v[176:179], v[192:195], 0
	v_mfma_f32_16x16x32_bf16 v[12:15], v[168:171], v[200:203], 0
	v_mfma_f32_16x16x32_bf16 v[8:11], v[176:179], v[200:203], 0
	v_mfma_f32_16x16x32_bf16 v[4:7], v[168:171], v[208:211], 0
	v_mfma_f32_16x16x32_bf16 v[0:3], v[176:179], v[208:211], 0
	v_mfma_f32_16x16x32_bf16 v[44:47], v[172:175], v[188:191], v[44:47]
	v_mfma_f32_16x16x32_bf16 v[40:43], v[180:183], v[188:191], v[40:43]
	v_mfma_f32_16x16x32_bf16 v[28:31], v[172:175], v[196:199], v[28:31]
	v_mfma_f32_16x16x32_bf16 v[24:27], v[180:183], v[196:199], v[24:27]
	v_mfma_f32_16x16x32_bf16 v[12:15], v[172:175], v[204:207], v[12:15]
	v_mfma_f32_16x16x32_bf16 v[8:11], v[180:183], v[204:207], v[8:11]
	v_mfma_f32_16x16x32_bf16 v[4:7], v[172:175], v[212:215], v[4:7]
	v_mfma_f32_16x16x32_bf16 v[0:3], v[180:183], v[212:215], v[0:3]
	s_setprio 0
	s_barrier
	s_add_i32 s47, 0, 0x18000
	v_add_u32_e32 v151, s47, v146
	s_add_i32 s48, 0, 0x1c000
	ds_read_b128 v[152:155], v151
	ds_read_b128 v[156:159], v151 offset:1024
	ds_read_b128 v[160:163], v151 offset:2048
	ds_read_b128 v[164:167], v151 offset:3072
	v_add_u32_e32 v151, s48, v146
	ds_read_b128 v[168:171], v151
	ds_read_b128 v[172:175], v151 offset:1024
	ds_read_b128 v[176:179], v151 offset:2048
	ds_read_b128 v[180:183], v151 offset:3072
	s_add_u32 s22, s22, 0x40000
	s_addc_u32 s23, s23, 0
	s_mov_b32 m0, s30
	v_lshl_add_u64 v[224:225], s[22:23], 0, v[134:135]
	ds_read_b128 v[184:187], v150 offset:32768
	ds_read_b128 v[188:191], v150 offset:33792
	ds_read_b128 v[192:195], v150 offset:34816
	ds_read_b128 v[196:199], v150 offset:35840
	ds_read_b128 v[200:203], v150 offset:36864
	ds_read_b128 v[204:207], v150 offset:37888
	ds_read_b128 v[208:211], v150 offset:38912
	ds_read_b128 v[212:215], v150 offset:39936
	global_load_lds_dwordx4 v[224:225], off
	v_lshl_add_u64 v[224:225], s[22:23], 0, v[130:131]
	s_mov_b32 m0, s31
	s_nop 0
	global_load_lds_dwordx4 v[224:225], off
	s_waitcnt vmcnt(8)
	s_waitcnt lgkmcnt(0)
	s_barrier
	s_setprio 1
	s_waitcnt lgkmcnt(0)
	v_mfma_f32_16x16x32_bf16 v[124:127], v[152:155], v[184:187], v[124:127]
	v_mfma_f32_16x16x32_bf16 v[120:123], v[160:163], v[184:187], v[120:123]
	v_mfma_f32_16x16x32_bf16 v[116:119], v[152:155], v[192:195], v[116:119]
	v_mfma_f32_16x16x32_bf16 v[112:115], v[160:163], v[192:195], v[112:115]
	v_mfma_f32_16x16x32_bf16 v[100:103], v[152:155], v[200:203], v[100:103]
	v_mfma_f32_16x16x32_bf16 v[96:99], v[160:163], v[200:203], v[96:99]
	v_mfma_f32_16x16x32_bf16 v[84:87], v[152:155], v[208:211], v[84:87]
	v_mfma_f32_16x16x32_bf16 v[80:83], v[160:163], v[208:211], v[80:83]
	v_mfma_f32_16x16x32_bf16 v[124:127], v[156:159], v[188:191], v[124:127]
	v_mfma_f32_16x16x32_bf16 v[120:123], v[164:167], v[188:191], v[120:123]
	v_mfma_f32_16x16x32_bf16 v[116:119], v[156:159], v[196:199], v[116:119]
	v_mfma_f32_16x16x32_bf16 v[112:115], v[164:167], v[196:199], v[112:115]
	v_mfma_f32_16x16x32_bf16 v[100:103], v[156:159], v[204:207], v[100:103]
	v_mfma_f32_16x16x32_bf16 v[96:99], v[164:167], v[204:207], v[96:99]
	v_mfma_f32_16x16x32_bf16 v[84:87], v[156:159], v[212:215], v[84:87]
	v_mfma_f32_16x16x32_bf16 v[80:83], v[164:167], v[212:215], v[80:83]
	s_setprio 0
	s_setprio 1
	v_mfma_f32_16x16x32_bf16 v[108:111], v[168:171], v[184:187], v[108:111]
	v_mfma_f32_16x16x32_bf16 v[104:107], v[176:179], v[184:187], v[104:107]
	v_mfma_f32_16x16x32_bf16 v[92:95], v[168:171], v[192:195], v[92:95]
	v_mfma_f32_16x16x32_bf16 v[88:91], v[176:179], v[192:195], v[88:91]
	v_mfma_f32_16x16x32_bf16 v[76:79], v[168:171], v[200:203], v[76:79]
	v_mfma_f32_16x16x32_bf16 v[72:75], v[176:179], v[200:203], v[72:75]
	v_mfma_f32_16x16x32_bf16 v[68:71], v[168:171], v[208:211], v[68:71]
	v_mfma_f32_16x16x32_bf16 v[64:67], v[176:179], v[208:211], v[64:67]
	v_mfma_f32_16x16x32_bf16 v[108:111], v[172:175], v[188:191], v[108:111]
	v_mfma_f32_16x16x32_bf16 v[104:107], v[180:183], v[188:191], v[104:107]
	v_mfma_f32_16x16x32_bf16 v[92:95], v[172:175], v[196:199], v[92:95]
	v_mfma_f32_16x16x32_bf16 v[88:91], v[180:183], v[196:199], v[88:91]
	v_mfma_f32_16x16x32_bf16 v[76:79], v[172:175], v[204:207], v[76:79]
	v_mfma_f32_16x16x32_bf16 v[72:75], v[180:183], v[204:207], v[72:75]
	v_mfma_f32_16x16x32_bf16 v[68:71], v[172:175], v[212:215], v[68:71]
	v_mfma_f32_16x16x32_bf16 v[64:67], v[180:183], v[212:215], v[64:67]
	s_setprio 0
	s_barrier
	s_add_i32 s22, s47, s26
	v_lshl_add_u64 v[216:217], v[216:217], 0, s[4:5]
	s_mov_b32 m0, s22
	ds_read_b128 v[184:187], v150 offset:49152
	ds_read_b128 v[188:191], v150 offset:50176
	ds_read_b128 v[192:195], v150 offset:51200
	ds_read_b128 v[196:199], v150 offset:52224
	ds_read_b128 v[200:203], v150 offset:53248
	ds_read_b128 v[204:207], v150 offset:54272
	ds_read_b128 v[208:211], v150 offset:55296
	ds_read_b128 v[212:215], v150 offset:56320
	global_load_lds_dwordx4 v[216:217], off
	s_add_i32 m0, s22, 0x2000
	s_add_u32 s20, s20, 0x40080
	v_lshl_add_u64 v[216:217], v[218:219], 0, s[4:5]
	s_addc_u32 s21, s21, 0
	s_add_i32 s22, s48, s26
	global_load_lds_dwordx4 v[216:217], off
	v_lshl_add_u64 v[216:217], s[20:21], 0, v[132:133]
	s_mov_b32 m0, s22
	s_nop 0
	global_load_lds_dwordx4 v[216:217], off
	v_lshl_add_u64 v[216:217], s[20:21], 0, v[128:129]
	s_add_i32 m0, s22, 0x2000
	s_nop 0
	global_load_lds_dwordx4 v[216:217], off
	v_lshl_add_u64 v[216:217], v[220:221], 0, s[4:5]
	s_mov_b32 m0, s34
	s_nop 0
	global_load_lds_dwordx4 v[216:217], off
	v_lshl_add_u64 v[216:217], v[222:223], 0, s[4:5]
	s_mov_b32 m0, s35
	s_nop 0
	global_load_lds_dwordx4 v[216:217], off
	s_waitcnt vmcnt(8)
	s_waitcnt lgkmcnt(0)
	s_barrier
	s_setprio 1
	s_waitcnt lgkmcnt(0)
	v_mfma_f32_16x16x32_bf16 v[60:63], v[152:155], v[184:187], v[60:63]
	v_mfma_f32_16x16x32_bf16 v[56:59], v[160:163], v[184:187], v[56:59]
	v_mfma_f32_16x16x32_bf16 v[52:55], v[152:155], v[192:195], v[52:55]
	v_mfma_f32_16x16x32_bf16 v[48:51], v[160:163], v[192:195], v[48:51]
	v_mfma_f32_16x16x32_bf16 v[36:39], v[152:155], v[200:203], v[36:39]
	v_mfma_f32_16x16x32_bf16 v[32:35], v[160:163], v[200:203], v[32:35]
	v_mfma_f32_16x16x32_bf16 v[20:23], v[152:155], v[208:211], v[20:23]
	v_mfma_f32_16x16x32_bf16 v[16:19], v[160:163], v[208:211], v[16:19]
	v_mfma_f32_16x16x32_bf16 v[60:63], v[156:159], v[188:191], v[60:63]
	v_mfma_f32_16x16x32_bf16 v[56:59], v[164:167], v[188:191], v[56:59]
	v_mfma_f32_16x16x32_bf16 v[52:55], v[156:159], v[196:199], v[52:55]
	v_mfma_f32_16x16x32_bf16 v[48:51], v[164:167], v[196:199], v[48:51]
	v_mfma_f32_16x16x32_bf16 v[36:39], v[156:159], v[204:207], v[36:39]
	v_mfma_f32_16x16x32_bf16 v[32:35], v[164:167], v[204:207], v[32:35]
	v_mfma_f32_16x16x32_bf16 v[20:23], v[156:159], v[212:215], v[20:23]
	v_mfma_f32_16x16x32_bf16 v[16:19], v[164:167], v[212:215], v[16:19]
	s_setprio 0
	s_setprio 1
	v_mfma_f32_16x16x32_bf16 v[44:47], v[168:171], v[184:187], v[44:47]
	v_mfma_f32_16x16x32_bf16 v[40:43], v[176:179], v[184:187], v[40:43]
	v_mfma_f32_16x16x32_bf16 v[28:31], v[168:171], v[192:195], v[28:31]
	v_mfma_f32_16x16x32_bf16 v[24:27], v[176:179], v[192:195], v[24:27]
	v_mfma_f32_16x16x32_bf16 v[12:15], v[168:171], v[200:203], v[12:15]
	v_mfma_f32_16x16x32_bf16 v[8:11], v[176:179], v[200:203], v[8:11]
	v_mfma_f32_16x16x32_bf16 v[4:7], v[168:171], v[208:211], v[4:7]
	v_mfma_f32_16x16x32_bf16 v[0:3], v[176:179], v[208:211], v[0:3]
	v_mfma_f32_16x16x32_bf16 v[44:47], v[172:175], v[188:191], v[44:47]
	v_mfma_f32_16x16x32_bf16 v[40:43], v[180:183], v[188:191], v[40:43]
	v_mfma_f32_16x16x32_bf16 v[28:31], v[172:175], v[196:199], v[28:31]
	v_mfma_f32_16x16x32_bf16 v[24:27], v[180:183], v[196:199], v[24:27]
	v_mfma_f32_16x16x32_bf16 v[12:15], v[172:175], v[204:207], v[12:15]
	v_mfma_f32_16x16x32_bf16 v[8:11], v[180:183], v[204:207], v[8:11]
	v_mfma_f32_16x16x32_bf16 v[4:7], v[172:175], v[212:215], v[4:7]
	v_mfma_f32_16x16x32_bf16 v[0:3], v[180:183], v[212:215], v[0:3]
	s_setprio 0
	s_barrier
	s_add_i32 s46, s46, 2
	s_add_u32 s18, s18, 0x100
	s_addc_u32 s19, s19, 0
	s_add_u32 s44, s44, 0x100
	s_addc_u32 s45, s45, 0
